# grid barrier code deduplicated: two shared barrier routines (stub + dispatch) instead of 22 inlined copies, hot in I-cache
# speedup vs baseline: 1.0185x; 1.0054x over previous
.LBB0_265:
	s_cmp_lt_i32 s2, 2
	s_cselect_b64 s[0:1], -1, 0
	s_cmp_gt_i32 s3, 1
	s_cselect_b64 s[2:3], -1, 0
	s_and_b64 s[2:3], s[0:1], s[2:3]
	s_andn2_b64 vcc, exec, s[2:3]
	s_cbranch_vccnz .LBB0_494
	s_andn2_b64 vcc, exec, s[24:25]
	s_cbranch_vccnz .LBB0_316
	v_writelane_b32 v255, s0, 58
	v_writelane_b32 v255, s1, 59
	v_writelane_b32 v255, 1, 61
	s_branch .Lbar_shared_A
.Lbar_ret_1:
	v_readlane_b32 s0, v255, 58
	v_readlane_b32 s1, v255, 59
	s_nop 3

.LBB0_494:
	v_readlane_b32 s2, v254, 0
	v_readlane_b32 s3, v254, 1
	s_cmp_lt_i32 s2, 3
	s_cselect_b64 s[10:11], -1, 0
	s_cmp_gt_i32 s3, 2
	s_cselect_b64 s[2:3], -1, 0
	s_and_b64 s[2:3], s[10:11], s[2:3]
	s_andn2_b64 vcc, exec, s[2:3]
	s_cbranch_vccnz .LBB0_595
	s_andn2_b64 vcc, exec, s[0:1]
	s_cbranch_vccnz .LBB0_545
	v_writelane_b32 v255, s10, 58
	v_writelane_b32 v255, s11, 59
	v_writelane_b32 v255, 2, 61
	s_branch .Lbar_shared_A
.Lbar_ret_2:
	v_readlane_b32 s10, v255, 58
	v_readlane_b32 s11, v255, 59
	s_nop 3

.LBB0_595:
	v_readlane_b32 s0, v254, 0
	v_readlane_b32 s1, v254, 1
	s_cmp_lt_i32 s0, 4
	s_cselect_b64 s[24:25], -1, 0
	s_cmp_gt_i32 s1, 3
	s_cselect_b64 s[0:1], -1, 0
	s_and_b64 s[0:1], s[24:25], s[0:1]
	s_andn2_b64 vcc, exec, s[0:1]
	s_cbranch_vccnz .LBB0_729
	s_andn2_b64 vcc, exec, s[10:11]
	s_cbranch_vccnz .LBB0_646
	v_writelane_b32 v255, s24, 58
	v_writelane_b32 v255, 3, 61
	s_branch .Lbar_shared_A
.Lbar_ret_3:
	v_readlane_b32 s24, v255, 58
	s_nop 3

.LBB0_729:
	v_readlane_b32 s0, v254, 0
	v_readlane_b32 s1, v254, 1
	s_cmp_lt_i32 s0, 5
	s_cselect_b64 s[4:5], -1, 0
	s_cmp_gt_i32 s1, 4
	s_cselect_b64 s[0:1], -1, 0
	s_and_b64 s[0:1], s[4:5], s[0:1]
	s_andn2_b64 vcc, exec, s[0:1]
	s_cbranch_vccnz .LBB0_825
	s_andn2_b64 vcc, exec, s[24:25]
	s_cbranch_vccnz .LBB0_780
	v_writelane_b32 v255, s4, 58
	v_writelane_b32 v255, s5, 59
	v_writelane_b32 v255, 4, 61
	s_branch .Lbar_shared_A
.Lbar_ret_4:
	v_readlane_b32 s4, v255, 58
	v_readlane_b32 s5, v255, 59
	s_nop 3

.LBB0_825:
	v_readlane_b32 s0, v254, 0
	v_readlane_b32 s1, v254, 1
	s_cmp_lt_i32 s0, 6
	s_cselect_b64 s[6:7], -1, 0
	s_cmp_gt_i32 s1, 5
	s_cselect_b64 s[0:1], -1, 0
	s_and_b64 s[0:1], s[6:7], s[0:1]
	s_andn2_b64 vcc, exec, s[0:1]
	s_cbranch_vccnz .LBB0_931
	s_andn2_b64 vcc, exec, s[4:5]
	s_cbranch_vccnz .LBB0_876
	v_writelane_b32 v255, 5, 61
.Lbar_shared_A:
	s_waitcnt vmcnt(0)
	v_cmp_eq_u32_e32 vcc, 0, v204
	s_waitcnt vmcnt(0)
	s_barrier
	s_and_saveexec_b64 s[0:1], vcc
	s_cbranch_execz .LBB0_875
	s_add_i32 s2, 0, 0x23fc0
	v_mov_b32_e32 v0, s2
	s_waitcnt vmcnt(0) expcnt(0) lgkmcnt(0)
	ds_read_b32 v2, v0
	s_add_i32 s2, 0, 0x23fc4
	v_mov_b32_e32 v0, s2
	ds_read_b32 v0, v0
	s_waitcnt lgkmcnt(1)
	v_cmp_ne_u32_e32 vcc, 0, v2
	s_cbranch_vccnz .LBB0_843
	s_load_dwordx2 s[8:9], s[78:79], 0x118
	s_load_dword s5, s[78:79], 0x120
	s_add_u32 s2, s90, 0x1000
	s_addc_u32 s3, s91, 0
	s_add_u32 s4, s90, 0x1100
	s_waitcnt lgkmcnt(0)
	s_mul_i32 s18, s9, s8
	s_mul_i32 s18, s18, s5
	s_addc_u32 s5, s91, 0
	s_add_u32 s8, s90, 0x1200
	s_addc_u32 s9, s91, 0
	s_add_u32 s10, s90, 0x1300
	s_addc_u32 s11, s91, 0
	s_mov_b32 s19, 1
	v_mov_b32_e32 v16, 0
	s_branch .LBB0_831

.LBB0_875:
	s_or_b64 exec, exec, s[0:1]
	s_waitcnt lgkmcnt(0)
	s_barrier
	v_readlane_b32 s2, v255, 61
	s_nop 3
	s_cmp_eq_u32 s2, 1
	s_cbranch_scc1 .Lbar_ret_1
	s_cmp_eq_u32 s2, 2
	s_cbranch_scc1 .Lbar_ret_2
	s_cmp_eq_u32 s2, 3
	s_cbranch_scc1 .Lbar_ret_3
	s_cmp_eq_u32 s2, 4
	s_cbranch_scc1 .Lbar_ret_4
	s_cmp_eq_u32 s2, 6
	s_cbranch_scc1 .Lbar_ret_6
	s_cmp_eq_u32 s2, 7
	s_cbranch_scc1 .Lbar_ret_7
	s_cmp_eq_u32 s2, 8
	s_cbranch_scc1 .Lbar_ret_8
	s_cmp_eq_u32 s2, 9
	s_cbranch_scc1 .Lbar_ret_9
	s_cmp_eq_u32 s2, 10
	s_cbranch_scc1 .Lbar_ret_10
	s_cmp_eq_u32 s2, 11
	s_cbranch_scc1 .Lbar_ret_11
	s_cmp_eq_u32 s2, 12
	s_cbranch_scc1 .Lbar_ret_12
.Lbar_ret_5:
.LBB0_876:
	v_readfirstlane_b32 s3, v204
	s_load_dword s9, s[78:79], 0x118
	s_lshr_b32 s2, s3, 6
	v_lshlrev_b32_e32 v1, 4, v204
	v_and_b32_e32 v0, 32, v204
	s_add_u32 s4, s90, 0x9a00000
	v_bfe_u32 v8, v204, 2, 4
	v_bitop3_b32 v179, v1, v0, 48 bitop3:0x6c
	v_lshrrev_b32_e32 v0, 3, v204
	s_movk_i32 s0, 0x70
	v_add_u32_e32 v9, 0x2000, v1
	s_addc_u32 s5, s91, 0
	v_and_b32_e32 v180, 64, v204
	v_and_or_b32 v184, v0, s0, v8
	v_lshrrev_b32_e32 v1, 7, v9
	s_movk_i32 s0, 0xf0
	s_lshl_b32 s8, s2, 5
	v_lshlrev_b32_e32 v2, 6, v204
	v_lshlrev_b32_e32 v178, 2, v204
	v_or_b32_e32 v183, v179, v180
	v_and_or_b32 v185, v1, s0, v8
	v_and_b32_e32 v176, 15, v204
	v_lshrrev_b32_e32 v177, 1, v204
	v_and_b32_e32 v181, 0x3c0, v2
	s_cmpk_gt_i32 s80, 0x7f
	v_and_b32_e32 v182, 32, v178
	s_cbranch_scc1 .LBB0_900
	s_ashr_i32 s33, s80, 31
	s_lshr_b32 s0, s33, 29
	s_add_i32 s11, s80, s0
	s_and_b32 s0, s11, -8
	s_sub_i32 s12, s80, s0
	s_cmp_gt_i32 s12, -1
	s_cbranch_scc0 .LBB0_879
	s_lshl_b32 s10, s12, 4
	v_lshrrev_b32_e32 v2, 2, v204
	s_ashr_i32 s11, s11, 3
	s_cbranch_execz .LBB0_880
	s_branch .LBB0_881

.LBB0_931:
	v_readlane_b32 s2, v254, 0
	v_readlane_b32 s3, v254, 1
	s_cmp_lt_i32 s2, 7
	s_cselect_b64 s[0:1], -1, 0
	s_cmp_gt_i32 s3, 6
	s_cselect_b64 s[2:3], -1, 0
	s_and_b64 s[2:3], s[0:1], s[2:3]
	s_andn2_b64 vcc, exec, s[2:3]
	s_cbranch_vccnz .LBB0_1020
	s_andn2_b64 vcc, exec, s[6:7]
	s_cbranch_vccnz .LBB0_982
	v_writelane_b32 v255, s0, 58
	v_writelane_b32 v255, s1, 59
	v_writelane_b32 v255, 6, 61
	s_branch .Lbar_shared_A

.LBB0_1020:
	v_readlane_b32 s2, v254, 0
	v_readlane_b32 s3, v254, 1
	s_cmp_lt_i32 s2, 8
	s_cselect_b64 s[4:5], -1, 0
	s_cmp_gt_i32 s3, 7
	s_cselect_b64 s[2:3], -1, 0
	s_and_b64 s[2:3], s[4:5], s[2:3]
	s_andn2_b64 vcc, exec, s[2:3]
	s_cbranch_vccnz .LBB0_1117
	s_andn2_b64 vcc, exec, s[0:1]
	s_cbranch_vccnz .LBB0_1071
	v_writelane_b32 v255, s4, 58
	v_writelane_b32 v255, s5, 59
	v_writelane_b32 v255, 7, 61
	s_branch .Lbar_shared_A

.LBB0_1117:
	v_readlane_b32 s2, v254, 0
	v_readlane_b32 s3, v254, 1
	s_cmp_lt_i32 s2, 9
	s_cselect_b64 s[0:1], -1, 0
	s_cmp_gt_i32 s3, 8
	s_cselect_b64 s[2:3], -1, 0
	s_and_b64 s[2:3], s[0:1], s[2:3]
	s_andn2_b64 vcc, exec, s[2:3]
	s_cbranch_vccnz .LBB0_1175
	s_andn2_b64 vcc, exec, s[4:5]
	s_cbranch_vccnz .LBB0_1168
	v_writelane_b32 v255, s0, 58
	v_writelane_b32 v255, s1, 59
	v_writelane_b32 v255, 8, 61
	s_branch .Lbar_shared_A

.LBB0_1175:
	v_readlane_b32 s2, v254, 0
	v_readlane_b32 s3, v254, 1
	s_cmp_lt_i32 s2, 10
	s_cselect_b64 s[4:5], -1, 0
	s_cmp_gt_i32 s3, 9
	s_cselect_b64 s[2:3], -1, 0
	s_and_b64 s[2:3], s[4:5], s[2:3]
	s_andn2_b64 vcc, exec, s[2:3]
	s_cbranch_vccnz .LBB0_1250
	s_andn2_b64 vcc, exec, s[0:1]
	s_cbranch_vccnz .LBB0_1226
	v_writelane_b32 v255, s4, 58
	v_writelane_b32 v255, s5, 59
	v_writelane_b32 v255, 9, 61
	s_branch .Lbar_shared_A

.LBB0_1250:
	v_readlane_b32 s2, v254, 0
	v_readlane_b32 s3, v254, 1
	s_cmp_lt_i32 s2, 11
	s_cselect_b64 s[0:1], -1, 0
	s_cmp_gt_i32 s3, 10
	s_cselect_b64 s[2:3], -1, 0
	s_and_b64 s[2:3], s[0:1], s[2:3]
	s_andn2_b64 vcc, exec, s[2:3]
	s_cbranch_vccnz .LBB0_1359
	s_andn2_b64 vcc, exec, s[4:5]
	s_cbranch_vccnz .LBB0_1301
	v_writelane_b32 v255, s0, 58
	v_writelane_b32 v255, s1, 59
	v_writelane_b32 v255, 10, 61
	s_branch .Lbar_shared_A

.LBB0_1359:
	v_readlane_b32 s2, v254, 0
	v_readlane_b32 s3, v254, 1
	s_cmp_lt_i32 s2, 12
	s_cselect_b64 s[4:5], -1, 0
	s_cmp_gt_i32 s3, 11
	s_cselect_b64 s[2:3], -1, 0
	s_and_b64 s[2:3], s[4:5], s[2:3]
	s_andn2_b64 vcc, exec, s[2:3]
	s_cbranch_vccnz .LBB0_1417
	s_andn2_b64 vcc, exec, s[0:1]
	s_cbranch_vccnz .LBB0_1410
	v_writelane_b32 v255, s4, 58
	v_writelane_b32 v255, s5, 59
	v_writelane_b32 v255, 11, 61
	s_branch .Lbar_shared_A

.LBB0_1417:
	v_readlane_b32 s2, v254, 0
	v_readlane_b32 s3, v254, 1
	s_cmp_lt_i32 s2, 13
	s_cselect_b64 s[0:1], -1, 0
	s_cmp_gt_i32 s3, 12
	s_cselect_b64 s[2:3], -1, 0
	s_and_b64 s[2:3], s[0:1], s[2:3]
	s_andn2_b64 vcc, exec, s[2:3]
	s_cbranch_vccnz .LBB0_1646
	s_andn2_b64 vcc, exec, s[4:5]
	s_cbranch_vccnz .LBB0_1468
	v_writelane_b32 v255, s0, 58
	v_writelane_b32 v255, s1, 59
	v_writelane_b32 v255, 12, 61
	s_branch .Lbar_shared_A

.LBB0_1646:
	v_readlane_b32 s2, v254, 0
	v_readlane_b32 s3, v254, 1
	s_cmp_lt_i32 s2, 14
	s_cselect_b64 s[10:11], -1, 0
	s_cmp_gt_i32 s3, 13
	s_cselect_b64 s[2:3], -1, 0
	s_and_b64 s[2:3], s[10:11], s[2:3]
	s_andn2_b64 vcc, exec, s[2:3]
	s_cbranch_vccnz .LBB0_1747
	s_andn2_b64 vcc, exec, s[0:1]
	s_cbranch_vccnz .LBB0_1697
	v_writelane_b32 v255, s10, 58
	v_writelane_b32 v255, s11, 59
	v_writelane_b32 v255, 13, 61
	s_branch .Lbar_shared_B

.LBB0_1747:
	v_readlane_b32 s0, v254, 0
	v_readlane_b32 s1, v254, 1
	s_cmp_lt_i32 s0, 15
	s_cselect_b64 s[68:69], -1, 0
	s_cmp_gt_i32 s1, 14
	s_cselect_b64 s[0:1], -1, 0
	s_and_b64 s[0:1], s[68:69], s[0:1]
	s_andn2_b64 vcc, exec, s[0:1]
	s_cbranch_vccnz .LBB0_1881
	s_andn2_b64 vcc, exec, s[10:11]
	s_cbranch_vccnz .LBB0_1798
	v_writelane_b32 v255, 14, 61
	s_branch .Lbar_shared_B
.Lbar_ret_14:
.LBB0_1798:
	s_load_dword s92, s[78:79], 0x118
	v_readfirstlane_b32 s10, v204
	s_mov_b32 s95, 0
	s_movk_i32 s0, 0x70f
	s_mov_b32 s94, 0
	s_waitcnt lgkmcnt(0)
	s_cmpk_lg_i32 s92, 0x100
	s_mov_b32 s93, 0
	s_mov_b32 s2, 0
	s_cbranch_scc1 .LBB0_1813
	s_cmp_gt_i32 s80, 15
	s_cbranch_scc0 .LBB0_1803
	s_cmp_gt_u32 s80, 59
	s_cbranch_scc0 .LBB0_1804
	s_cmpk_gt_u32 s80, 0xe3
	s_cbranch_scc0 .LBB0_1805
	s_add_i32 s93, s80, 0xf0
	s_mov_b64 s[0:1], 0
	s_branch .LBB0_1806

.LBB0_1881:
	v_readlane_b32 s0, v254, 0
	v_readlane_b32 s1, v254, 1
	s_cmp_lt_i32 s0, 16
	s_cselect_b64 s[4:5], -1, 0
	s_cmp_gt_i32 s1, 15
	s_cselect_b64 s[0:1], -1, 0
	s_and_b64 s[0:1], s[4:5], s[0:1]
	s_andn2_b64 vcc, exec, s[0:1]
	s_cbranch_vccnz .LBB0_1977
	s_andn2_b64 vcc, exec, s[68:69]
	s_cbranch_vccnz .LBB0_1932
	v_writelane_b32 v255, s4, 58
	v_writelane_b32 v255, s5, 59
	v_writelane_b32 v255, 15, 61
	s_branch .Lbar_shared_B

.LBB0_1977:
	v_readlane_b32 s0, v254, 0
	v_readlane_b32 s1, v254, 1
	s_cmp_lt_i32 s0, 17
	s_cselect_b64 s[6:7], -1, 0
	s_cmp_gt_i32 s1, 16
	s_cselect_b64 s[0:1], -1, 0
	s_and_b64 s[0:1], s[6:7], s[0:1]
	s_andn2_b64 vcc, exec, s[0:1]
	s_cbranch_vccnz .LBB0_2083
	s_andn2_b64 vcc, exec, s[4:5]
	s_cbranch_vccnz .LBB0_2028
	v_writelane_b32 v255, s6, 58
	v_writelane_b32 v255, s7, 59
	v_writelane_b32 v255, 16, 61
	s_branch .Lbar_shared_B
.Lbar_ret_16:
	v_readlane_b32 s6, v255, 58
	v_readlane_b32 s7, v255, 59
	s_nop 3

.LBB0_2083:
	v_readlane_b32 s2, v254, 0
	v_readlane_b32 s3, v254, 1
	s_cmp_lt_i32 s2, 18
	s_cselect_b64 s[0:1], -1, 0
	s_cmp_gt_i32 s3, 17
	s_cselect_b64 s[2:3], -1, 0
	s_and_b64 s[2:3], s[0:1], s[2:3]
	s_andn2_b64 vcc, exec, s[2:3]
	s_cbranch_vccnz .LBB0_2172
	s_andn2_b64 vcc, exec, s[6:7]
	s_cbranch_vccnz .LBB0_2134
	v_writelane_b32 v255, 17, 61
.Lbar_shared_B:
	s_waitcnt vmcnt(0)
	v_cmp_eq_u32_e32 vcc, 0, v204
	s_waitcnt vmcnt(0) lgkmcnt(0)
	s_barrier
	s_and_saveexec_b64 s[2:3], vcc
	s_cbranch_execz .LBB0_2133
	s_add_i32 s4, 0, 0x23fc0
	v_mov_b32_e32 v0, s4
	s_waitcnt vmcnt(0) expcnt(0) lgkmcnt(0)
	ds_read_b32 v2, v0
	s_add_i32 s4, 0, 0x23fc4
	v_mov_b32_e32 v0, s4
	ds_read_b32 v0, v0
	s_waitcnt lgkmcnt(1)
	v_cmp_ne_u32_e32 vcc, 0, v2
	s_cbranch_vccnz .LBB0_2101
	s_load_dwordx2 s[8:9], s[78:79], 0x118
	s_load_dword s7, s[78:79], 0x120
	s_add_u32 s4, s90, 0x1000
	s_addc_u32 s5, s91, 0
	s_add_u32 s6, s90, 0x1100
	s_waitcnt lgkmcnt(0)
	s_mul_i32 s18, s9, s8
	s_mul_i32 s18, s18, s7
	s_addc_u32 s7, s91, 0
	s_add_u32 s8, s90, 0x1200
	s_addc_u32 s9, s91, 0
	s_add_u32 s10, s90, 0x1300
	s_addc_u32 s11, s91, 0
	s_mov_b32 s19, 1
	v_mov_b32_e32 v16, 0
	s_branch .LBB0_2089

.LBB0_2133:
	s_or_b64 exec, exec, s[2:3]
	s_waitcnt lgkmcnt(0)
	s_barrier
	v_readlane_b32 s2, v255, 61
	s_nop 3
	s_cmp_eq_u32 s2, 13
	s_cbranch_scc1 .Lbar_ret_13
	s_cmp_eq_u32 s2, 14
	s_cbranch_scc1 .Lbar_ret_14
	s_cmp_eq_u32 s2, 15
	s_cbranch_scc1 .Lbar_ret_15
	s_cmp_eq_u32 s2, 16
	s_cbranch_scc1 .Lbar_ret_16
	s_cmp_eq_u32 s2, 18
	s_cbranch_scc1 .Lbar_ret_18
	s_cmp_eq_u32 s2, 19
	s_cbranch_scc1 .Lbar_ret_19
	s_cmp_eq_u32 s2, 20
	s_cbranch_scc1 .Lbar_ret_20
	s_cmp_eq_u32 s2, 21
	s_cbranch_scc1 .Lbar_ret_21
	s_cmp_eq_u32 s2, 22
	s_cbranch_scc1 .Lbar_ret_22
.Lbar_ret_17:
.LBB0_2134:
	s_waitcnt lgkmcnt(0)
	s_load_dword s33, s[78:79], 0x118
	s_cmpk_gt_i32 s80, 0xff
	v_readfirstlane_b32 s4, v204
	s_cbranch_scc1 .LBB0_2168
	s_ashr_i32 s34, s80, 31
	s_lshr_b32 s2, s34, 29
	s_add_i32 s7, s80, s2
	s_and_b32 s2, s7, -8
	s_sub_i32 s5, s80, s2
	s_cmp_gt_i32 s5, -1
	s_cbranch_scc0 .LBB0_2137
	s_lshl_b32 s6, s5, 5
	s_ashr_i32 s3, s7, 3
	s_cbranch_execz .LBB0_2138
	s_branch .LBB0_2139

.LBB0_2172:
	v_readlane_b32 s2, v254, 0
	v_readlane_b32 s3, v254, 1
	s_cmp_lt_i32 s2, 19
	s_cselect_b64 s[4:5], -1, 0
	s_cmp_gt_i32 s3, 18
	s_cselect_b64 s[2:3], -1, 0
	s_and_b64 s[2:3], s[4:5], s[2:3]
	s_andn2_b64 vcc, exec, s[2:3]
	s_cbranch_vccnz .LBB0_2269
	s_andn2_b64 vcc, exec, s[0:1]
	s_cbranch_vccnz .LBB0_2223
	v_writelane_b32 v255, s4, 58
	v_writelane_b32 v255, s5, 59
	v_writelane_b32 v255, 18, 61
	s_branch .Lbar_shared_B

.LBB0_2269:
	v_readlane_b32 s2, v254, 0
	v_readlane_b32 s3, v254, 1
	s_cmp_lt_i32 s2, 20
	s_cselect_b64 s[0:1], -1, 0
	s_cmp_gt_i32 s3, 19
	s_cselect_b64 s[2:3], -1, 0
	s_and_b64 s[2:3], s[0:1], s[2:3]
	s_andn2_b64 vcc, exec, s[2:3]
	s_cbranch_vccnz .LBB0_2327
	s_andn2_b64 vcc, exec, s[4:5]
	s_cbranch_vccnz .LBB0_2320
	v_writelane_b32 v255, 19, 61
	s_branch .Lbar_shared_B
.Lbar_ret_19:
.LBB0_2320:
	v_readfirstlane_b32 s2, v204
	s_lshr_b32 s2, s2, 6
	s_lshl_b32 s3, s80, 3
	s_add_i32 s4, s2, s3
	s_cmpk_gt_i32 s4, 0x41ff
	s_cbranch_scc1 .LBB0_2327
	s_load_dword s6, s[78:79], 0x118
	s_waitcnt vmcnt(0)
	v_and_b32_e32 v4, 63, v204
	v_mov_b32_e32 v1, 0
	v_lshlrev_b32_e32 v0, 4, v4
	v_lshl_add_u64 v[2:3], s[90:91], 0, v[0:1]
	s_waitcnt lgkmcnt(0)
	s_lshl_b32 s6, s6, 3
	s_mov_b64 s[8:9], 0x1d000000
	s_ashr_i32 s7, s3, 31
	v_lshl_add_u64 v[22:23], v[2:3], 0, s[8:9]
	v_lshlrev_b32_e32 v2, 3, v4
	v_mov_b32_e32 v3, v1
	s_add_u32 s2, s2, s3
	v_lshl_add_u64 v[2:3], s[90:91], 0, v[2:3]
	s_mov_b64 s[8:9], 0x5800000
	s_addc_u32 s3, 0, s7
	s_ashr_i32 s7, s6, 31
	v_lshl_add_u64 v[24:25], v[2:3], 0, s[8:9]
	s_lshl_b64 s[8:9], s[2:3], 10
	s_lshl_b64 s[10:11], s[6:7], 10
	s_lshl_b64 s[2:3], s[2:3], 12
	s_add_u32 s2, s88, s2
	s_addc_u32 s3, s89, s3
	v_lshl_add_u64 v[20:21], s[88:89], 0, v[0:1]
	v_lshl_add_u64 v[26:27], s[2:3], 0, v[0:1]
	v_mbcnt_lo_u32_b32 v0, -1, 0
	v_mbcnt_hi_u32_b32 v30, -1, v0
	v_and_b32_e32 v0, 64, v30
	s_mov_b32 s5, 0
	s_lshl_b64 s[12:13], s[6:7], 12
	s_mov_b32 s7, 0x200000
	s_mov_b32 s16, 0x400000
	s_mov_b32 s17, 0x600000
	s_mov_b32 s18, 0x800000
	s_mov_b32 s19, 0xa00000
	s_mov_b32 s20, 0xc00000
	s_mov_b32 s21, 0xe00000
	v_mov_b32_e32 v28, 0x358637bd
	s_mov_b32 s22, 0xf800000
	v_mov_b32_e32 v29, 0x260
	s_movk_i32 s23, 0x7fff
	v_add_u32_e32 v31, 64, v0
	v_xor_b32_e32 v32, 1, v30
	v_xor_b32_e32 v33, 2, v30
	v_xor_b32_e32 v34, 4, v30
	v_xor_b32_e32 v35, 8, v30
	v_xor_b32_e32 v36, 16, v30
	v_xor_b32_e32 v37, 32, v30
	v_mov_b32_e32 v38, 1
	s_branch .LBB0_2323

.LBB0_2327:
	v_readlane_b32 s2, v254, 0
	v_readlane_b32 s3, v254, 1
	s_cmp_lt_i32 s2, 21
	s_cselect_b64 s[4:5], -1, 0
	s_cmp_gt_i32 s3, 20
	s_cselect_b64 s[2:3], -1, 0
	s_and_b64 s[2:3], s[4:5], s[2:3]
	s_andn2_b64 vcc, exec, s[2:3]
	s_cbranch_vccnz .LBB0_2402
	s_andn2_b64 vcc, exec, s[0:1]
	s_cbranch_vccnz .LBB0_2378
	v_writelane_b32 v255, s4, 58
	v_writelane_b32 v255, s5, 59
	v_writelane_b32 v255, 20, 61
	s_branch .Lbar_shared_B

.LBB0_2402:
	v_readlane_b32 s2, v254, 0
	v_readlane_b32 s3, v254, 1
	s_cmp_lt_i32 s2, 22
	s_cselect_b64 s[0:1], -1, 0
	s_cmp_gt_i32 s3, 21
	s_cselect_b64 s[2:3], -1, 0
	s_and_b64 s[2:3], s[0:1], s[2:3]
	s_andn2_b64 vcc, exec, s[2:3]
	s_cbranch_vccnz .LBB0_2511
	s_andn2_b64 vcc, exec, s[4:5]
	s_cbranch_vccnz .LBB0_2453
	v_writelane_b32 v255, 21, 61
	s_branch .Lbar_shared_B
.Lbar_ret_21:
.LBB0_2453:
	s_cmpk_lt_i32 s80, 0x100
	s_cselect_b64 s[2:3], -1, 0
	s_cmpk_gt_i32 s80, 0xff
	v_readfirstlane_b32 s12, v204
	s_cbranch_scc1 .LBB0_2459
	s_ashr_i32 s4, s80, 31
	s_lshr_b32 s4, s4, 29
	s_add_i32 s8, s80, s4
	s_and_b32 s4, s8, -8
	s_sub_i32 s6, s80, s4
	s_cmp_gt_i32 s6, -1
	s_cbranch_scc0 .LBB0_2456
	s_lshl_b32 s7, s6, 5
	s_ashr_i32 s4, s8, 3
	s_cbranch_execz .LBB0_2457
	s_branch .LBB0_2458

.LBB0_2511:
	v_readlane_b32 s4, v254, 0
	v_readlane_b32 s5, v254, 1
	s_cmp_lt_i32 s4, 23
	s_cselect_b64 s[2:3], -1, 0
	s_cmp_gt_i32 s5, 22
	s_cselect_b64 s[4:5], -1, 0
	s_and_b64 s[2:3], s[2:3], s[4:5]
	s_andn2_b64 vcc, exec, s[2:3]
	s_cbranch_vccnz .LBB0_2569
	s_andn2_b64 vcc, exec, s[0:1]
	s_cbranch_vccnz .LBB0_2562
	v_writelane_b32 v255, 22, 61
	s_branch .Lbar_shared_B
.Lbar_ret_22:
.LBB0_2562:
	v_readfirstlane_b32 s0, v204
	s_lshr_b32 s0, s0, 6
	s_lshl_b32 s1, s80, 3
	s_add_i32 s2, s1, s0
	s_add_i32 s0, s2, 0x4000
	s_cmpk_gt_i32 s0, 0x41ff
	s_cbranch_scc1 .LBB0_2569
	s_load_dword s1, s[78:79], 0x118
	s_waitcnt vmcnt(0)
	v_and_b32_e32 v4, 63, v204
	v_mov_b32_e32 v1, 0
	v_lshlrev_b32_e32 v0, 4, v4
	v_lshl_add_u64 v[2:3], s[90:91], 0, v[0:1]
	s_waitcnt lgkmcnt(0)
	s_lshl_b32 s4, s1, 3
	s_mov_b64 s[6:7], 0x1d000000
	s_ashr_i32 s1, s0, 31
	v_lshl_add_u64 v[34:35], v[2:3], 0, s[6:7]
	s_lshl_b64 s[6:7], s[0:1], 11
	s_add_u32 s6, s90, s6
	v_lshlrev_b32_e32 v2, 3, v4
	v_mov_b32_e32 v3, v1
	s_addc_u32 s7, s91, s7
	v_lshl_add_u64 v[2:3], s[6:7], 0, v[2:3]
	s_mov_b64 s[6:7], 0x5800000
	s_ashr_i32 s5, s4, 31
	v_lshl_add_u64 v[36:37], v[2:3], 0, s[6:7]
	s_lshl_b64 s[6:7], s[4:5], 11
	s_lshl_b64 s[0:1], s[0:1], 12
	s_add_u32 s0, s88, s0
	s_addc_u32 s1, s89, s1
	v_lshl_add_u64 v[32:33], s[88:89], 0, v[0:1]
	v_lshl_add_u64 v[38:39], s[0:1], 0, v[0:1]
	v_mbcnt_lo_u32_b32 v0, -1, 0
	s_lshl_b64 s[8:9], s[4:5], 12
	s_mov_b32 s11, 0
	s_mov_b32 s5, 0x200000
	s_mov_b32 s12, 0x400000
	s_mov_b32 s13, 0x600000
	s_mov_b32 s14, 0x800000
	s_mov_b32 s15, 0xa00000
	s_mov_b32 s16, 0xc00000
	s_mov_b32 s17, 0xe00000
	s_mov_b32 s18, 0x1000000
	s_mov_b32 s19, 0x1200000
	s_mov_b32 s20, 0x1400000
	v_mov_b32_e32 v44, 0x358637bd
	s_mov_b32 s21, 0xf800000
	v_mov_b32_e32 v45, 0x260
	s_movk_i32 s22, 0x7fff
	v_mbcnt_hi_u32_b32 v46, -1, v0
	v_mov_b32_e32 v47, 1
	s_branch .LBB0_2565
